# P6 branch GEMM: touch-ahead loads warm L2 for the gate lines of the hook and of the epilogue (one round trip instead of a chain)
# baseline (speedup 1.0000x reference)
; #define GAS __attribute__((address_space(1)))
; __device__ __forceinline__ float frcp(float x) { return __builtin_amdgcn_rcpf(x); }
; __device__ __forceinline__ void unpack8(u32x4 w, f32x4& a, f32x4& b) { a = (f32x4){bf_lo(w.x), bf_hi(w.x), bf_lo(w.y), bf_hi(w.y)}; b = (f32x4){bf_lo(w.z), bf_hi(w.z), bf_lo(w.w), bf_hi(w.w)}; }
;     __device__ __forceinline__ void hook(f32x4 (&acc)[2][2][4][2], const Unit& u, int seg, int wr, int wc, int fr, int fq) const {
;         const GAS bf16_t* gbase = Pg + (size_t)(u.pm * 256 + wr * 64 + fr) * PW + PC_GATE + (seg - 1) * 1024 + u.pn * 256 + wc * 32 + 8 * fq;
; #pragma unroll
;         for (int ai = 0; ai < 2; ++ai) {
;             u32x4 ga[4][2], gb[4][2];
; #pragma unroll
;             for (int m = 0; m < 4; ++m)
; #pragma unroll
;                 for (int bj = 0; bj < 2; ++bj) { const GAS bf16_t* gp = gbase + (size_t)(ai * 128 + m * 16) * PW + bj * 128;
;                     ga[m][bj] = *(const GAS u32x4*)gp; gb[m][bj] = *(const GAS u32x4*)(gp + 1024); }
; #pragma unroll
;             for (int m = 0; m < 4; ++m)
; #pragma unroll
;                 for (int bj = 0; bj < 2; ++bj) { f32x4 a0, a1, b0, b1; unpack8(ga[m][bj], a0, a1); unpack8(gb[m][bj], b0, b1);
; #pragma unroll
;                     for (int i = 0; i < 4; ++i) { acc[ai][bj][m][0][i] *= a0[i] * frcp(b0[i]); acc[ai][bj][m][1][i] *= a1[i] * frcp(b1[i]); } }
;             asm volatile("" ::: "memory");
;         }
;     }
.LBB0_1027:
	s_andn2_b64 vcc, exec, s[52:53]
	s_cbranch_vccnz .LBB0_1029
	s_mov_b32 s98, 0x28000
	s_mov_b32 s99, 0
	s_mov_b32 s100, 0xc8000
	s_mov_b32 s101, 0
	v_lshl_add_u64 v[242:243], v[182:183], 0, s[98:99]
	global_load_dword v246, v[242:243], off
	global_load_dword v246, v[242:243], off offset:256
	global_load_dword v246, v[242:243], off offset:2048
	global_load_dword v246, v[242:243], off offset:2304
	v_lshl_add_u64 v[242:243], v[242:243], 0, s[98:99]
	global_load_dword v246, v[242:243], off
	global_load_dword v246, v[242:243], off offset:256
	global_load_dword v246, v[242:243], off offset:2048
	global_load_dword v246, v[242:243], off offset:2304
	v_lshl_add_u64 v[242:243], v[242:243], 0, s[98:99]
	global_load_dword v246, v[242:243], off
	global_load_dword v246, v[242:243], off offset:256
	global_load_dword v246, v[242:243], off offset:2048
	global_load_dword v246, v[242:243], off offset:2304
	v_lshl_add_u64 v[242:243], v[242:243], 0, s[100:101]
	global_load_dword v246, v[242:243], off
	global_load_dword v246, v[242:243], off offset:256
	global_load_dword v246, v[242:243], off offset:2048
	global_load_dword v246, v[242:243], off offset:2304
	v_lshl_add_u64 v[242:243], v[242:243], 0, s[98:99]
	global_load_dword v246, v[242:243], off
	global_load_dword v246, v[242:243], off offset:256
	global_load_dword v246, v[242:243], off offset:2048
	global_load_dword v246, v[242:243], off offset:2304
	v_lshl_add_u64 v[242:243], v[242:243], 0, s[98:99]
	global_load_dword v246, v[242:243], off
	global_load_dword v246, v[242:243], off offset:256
	global_load_dword v246, v[242:243], off offset:2048
	global_load_dword v246, v[242:243], off offset:2304
	v_lshl_add_u64 v[242:243], v[242:243], 0, s[98:99]
	global_load_dword v246, v[242:243], off
	global_load_dword v246, v[242:243], off offset:256
	global_load_dword v246, v[242:243], off offset:2048
	global_load_dword v246, v[242:243], off offset:2304
	global_load_dwordx4 v[194:197], v[182:183], off offset:2048
	global_load_dwordx4 v[198:201], v[182:183], off
	global_load_dwordx4 v[202:205], v[182:183], off offset:2304
	global_load_dwordx4 v[206:209], v[182:183], off offset:256
	v_add_co_u32_e32 v128, vcc, 0x28000, v182
	s_waitcnt vmcnt(0)
	v_lshlrev_b32_e32 v193, 16, v194
	v_addc_co_u32_e32 v129, vcc, 0, v183, vcc
	global_load_dwordx4 v[210:213], v[128:129], off
	global_load_dwordx4 v[160:163], v[128:129], off offset:256
	global_load_dwordx4 v[214:217], v[128:129], off offset:2048
	global_load_dwordx4 v[218:221], v[128:129], off offset:2304
	v_add_co_u32_e32 v130, vcc, s71, v182
	v_and_b32_e32 v223, 0xffff0000, v194
	s_nop 0
	v_addc_co_u32_e32 v131, vcc, 0, v183, vcc
	global_load_dwordx4 v[152:155], v[130:131], off
	global_load_dwordx4 v[144:147], v[130:131], off offset:256
	global_load_dwordx4 v[156:159], v[130:131], off offset:2048
	global_load_dwordx4 v[148:151], v[130:131], off offset:2304
	v_add_co_u32_e32 v132, vcc, s72, v182
	v_lshlrev_b32_e32 v234, 16, v203
	s_nop 0
	v_addc_co_u32_e32 v133, vcc, 0, v183, vcc
	global_load_dwordx4 v[136:139], v[132:133], off
	global_load_dwordx4 v[128:131], v[132:133], off offset:256
	global_load_dwordx4 v[140:143], v[132:133], off offset:2048
	s_nop 0
	global_load_dwordx4 v[132:135], v[132:133], off offset:2304
	v_and_b32_e32 v235, 0xffff0000, v203
	v_rcp_f32_e32 v222, v193
	v_rcp_f32_e32 v223, v223
	v_rcp_f32_e32 v234, v234
	v_rcp_f32_e32 v235, v235
	v_lshlrev_b32_e32 v236, 16, v205
	v_and_b32_e32 v237, 0xffff0000, v205
	v_lshlrev_b32_e32 v226, 16, v195
	v_and_b32_e32 v227, 0xffff0000, v195
	v_lshlrev_b32_e32 v194, 16, v198
	v_and_b32_e32 v195, 0xffff0000, v198
	v_rcp_f32_e32 v236, v236
	v_rcp_f32_e32 v237, v237
	v_lshlrev_b32_e32 v224, 16, v196
	v_and_b32_e32 v225, 0xffff0000, v196
	v_lshlrev_b32_e32 v230, 16, v202
	v_and_b32_e32 v231, 0xffff0000, v202
	v_lshlrev_b32_e32 v202, 16, v206
	v_and_b32_e32 v203, 0xffff0000, v206
	v_lshlrev_b32_e32 v206, 16, v207
	v_pk_mul_f32 v[194:195], v[222:223], v[194:195]
	v_and_b32_e32 v207, 0xffff0000, v207
	v_rcp_f32_e32 v224, v224
	v_rcp_f32_e32 v225, v225
	v_pk_mul_f32 v[120:121], v[120:121], v[194:195]
	v_pk_mul_f32 v[194:195], v[234:235], v[206:207]
	v_rcp_f32_e32 v226, v226
	v_pk_mul_f32 v[118:119], v[118:119], v[194:195]
	v_lshlrev_b32_e32 v194, 16, v209
	v_and_b32_e32 v195, 0xffff0000, v209
	v_rcp_f32_e32 v227, v227
	v_pk_mul_f32 v[194:195], v[236:237], v[194:195]
	v_lshlrev_b32_e32 v228, 16, v197
	v_and_b32_e32 v229, 0xffff0000, v197
	v_lshlrev_b32_e32 v196, 16, v200
	v_and_b32_e32 v197, 0xffff0000, v200
	v_pk_mul_f32 v[114:115], v[114:115], v[194:195]
	v_pk_mul_f32 v[196:197], v[224:225], v[196:197]
	v_lshlrev_b32_e32 v198, 16, v199
	v_and_b32_e32 v199, 0xffff0000, v199
	v_rcp_f32_e32 v228, v228
	v_rcp_f32_e32 v229, v229
	v_pk_mul_f32 v[124:125], v[124:125], v[196:197]
	v_pk_mul_f32 v[198:199], v[226:227], v[198:199]
	v_rcp_f32_e32 v230, v230
	v_rcp_f32_e32 v231, v231
	v_pk_mul_f32 v[122:123], v[122:123], v[198:199]
	v_lshlrev_b32_e32 v200, 16, v201
	v_and_b32_e32 v201, 0xffff0000, v201
	v_pk_mul_f32 v[200:201], v[228:229], v[200:201]
	v_pk_mul_f32 v[202:203], v[230:231], v[202:203]
	v_pk_mul_f32 v[126:127], v[126:127], v[200:201]
	v_pk_mul_f32 v[116:117], v[116:117], v[202:203]
	v_lshlrev_b32_e32 v232, 16, v204
	v_and_b32_e32 v233, 0xffff0000, v204
	v_rcp_f32_e32 v232, v232
	v_rcp_f32_e32 v233, v233
	v_lshlrev_b32_e32 v204, 16, v208
	v_and_b32_e32 v205, 0xffff0000, v208
	v_pk_mul_f32 v[204:205], v[232:233], v[204:205]
	s_nop 0
	v_pk_mul_f32 v[112:113], v[112:113], v[204:205]
	s_waitcnt vmcnt(0)
; #define GAS __attribute__((address_space(1)))
; __device__ __forceinline__ float frcp(float x) { return __builtin_amdgcn_rcpf(x); }
; __device__ __forceinline__ void unpack8(u32x4 w, f32x4& a, f32x4& b) { a = (f32x4){bf_lo(w.x), bf_hi(w.x), bf_lo(w.y), bf_hi(w.y)}; b = (f32x4){bf_lo(w.z), bf_hi(w.z), bf_lo(w.w), bf_hi(w.w)}; }
;     __device__ __forceinline__ void hook(f32x4 (&acc)[2][2][4][2], const Unit& u, int seg, int wr, int wc, int fr, int fq) const {
;     ...
;                 for (int bj = 0; bj < 2; ++bj) { const GAS bf16_t* gp = gbase + (size_t)(ai * 128 + m * 16) * PW + bj * 128;
;                     ga[m][bj] = *(const GAS u32x4*)gp; gb[m][bj] = *(const GAS u32x4*)(gp + 1024); }
; #pragma unroll
;             for (int m = 0; m < 4; ++m)
; #pragma unroll
;                 for (int bj = 0; bj < 2; ++bj) { f32x4 a0, a1, b0, b1; unpack8(ga[m][bj], a0, a1); unpack8(gb[m][bj], b0, b1);
; #pragma unroll
;                     for (int i = 0; i < 4; ++i) { acc[ai][bj][m][0][i] *= a0[i] * frcp(b0[i]); acc[ai][bj][m][1][i] *= a1[i] * frcp(b1[i]); } }
	v_lshlrev_b32_e32 v198, 16, v210
	v_and_b32_e32 v199, 0xffff0000, v210
	v_lshlrev_b32_e32 v193, 16, v214
	v_and_b32_e32 v195, 0xffff0000, v214
	v_rcp_f32_e32 v194, v193
	v_rcp_f32_e32 v195, v195
	v_lshlrev_b32_e32 v196, 16, v216
	v_and_b32_e32 v197, 0xffff0000, v216
	v_rcp_f32_e32 v196, v196
	v_rcp_f32_e32 v197, v197
	v_pk_mul_f32 v[194:195], v[194:195], v[198:199]
	v_lshlrev_b32_e32 v200, 16, v215
	v_pk_mul_f32 v[108:109], v[108:109], v[194:195]
	v_lshlrev_b32_e32 v194, 16, v212
	v_and_b32_e32 v195, 0xffff0000, v212
	v_and_b32_e32 v201, 0xffff0000, v215
	v_pk_mul_f32 v[194:195], v[196:197], v[194:195]
	v_lshlrev_b32_e32 v202, 16, v217
	v_pk_mul_f32 v[104:105], v[104:105], v[194:195]
	v_rcp_f32_e32 v194, v200
	v_rcp_f32_e32 v195, v201
	v_and_b32_e32 v203, 0xffff0000, v217
	v_rcp_f32_e32 v196, v202
	v_rcp_f32_e32 v197, v203
	v_lshlrev_b32_e32 v198, 16, v211
	v_and_b32_e32 v199, 0xffff0000, v211
	v_pk_mul_f32 v[194:195], v[194:195], v[198:199]
	v_lshlrev_b32_e32 v193, 16, v218
	v_pk_mul_f32 v[110:111], v[110:111], v[194:195]
	v_lshlrev_b32_e32 v194, 16, v213
	v_and_b32_e32 v195, 0xffff0000, v213
	v_pk_mul_f32 v[194:195], v[196:197], v[194:195]
	v_lshlrev_b32_e32 v196, 16, v220
	v_pk_mul_f32 v[106:107], v[106:107], v[194:195]
	v_and_b32_e32 v195, 0xffff0000, v218
	v_rcp_f32_e32 v194, v193
	v_rcp_f32_e32 v195, v195
	v_and_b32_e32 v197, 0xffff0000, v220
	v_rcp_f32_e32 v196, v196
	v_rcp_f32_e32 v197, v197
	v_lshlrev_b32_e32 v198, 16, v160
	v_and_b32_e32 v199, 0xffff0000, v160
	v_pk_mul_f32 v[194:195], v[194:195], v[198:199]
	v_lshlrev_b32_e32 v202, 16, v221
	v_and_b32_e32 v203, 0xffff0000, v221
	v_pk_mul_f32 v[100:101], v[100:101], v[194:195]
	v_lshlrev_b32_e32 v194, 16, v162
	v_and_b32_e32 v195, 0xffff0000, v162
	v_pk_mul_f32 v[194:195], v[196:197], v[194:195]
	v_rcp_f32_e32 v160, v202
	v_lshlrev_b32_e32 v196, 16, v161
	v_and_b32_e32 v197, 0xffff0000, v161
	v_rcp_f32_e32 v161, v203
	v_lshlrev_b32_e32 v200, 16, v219
	v_and_b32_e32 v201, 0xffff0000, v219
	v_pk_mul_f32 v[96:97], v[96:97], v[194:195]
	v_rcp_f32_e32 v194, v200
	v_rcp_f32_e32 v195, v201
	v_lshlrev_b32_e32 v162, 16, v163
	v_and_b32_e32 v163, 0xffff0000, v163
	v_pk_mul_f32 v[160:161], v[160:161], v[162:163]
	v_pk_mul_f32 v[194:195], v[194:195], v[196:197]
	v_pk_mul_f32 v[98:99], v[98:99], v[160:161]
	v_lshlrev_b32_e32 v160, 16, v156
	v_and_b32_e32 v161, 0xffff0000, v156
	v_lshlrev_b32_e32 v162, 16, v157
	v_and_b32_e32 v163, 0xffff0000, v157
	v_rcp_f32_e32 v156, v160
	v_rcp_f32_e32 v157, v161
	v_pk_mul_f32 v[102:103], v[102:103], v[194:195]
	v_lshlrev_b32_e32 v193, 16, v158
	v_and_b32_e32 v194, 0xffff0000, v158
	v_lshlrev_b32_e32 v195, 16, v159
	v_and_b32_e32 v196, 0xffff0000, v159
	v_rcp_f32_e32 v158, v193
	v_rcp_f32_e32 v159, v194
	v_lshlrev_b32_e32 v160, 16, v152
	v_and_b32_e32 v161, 0xffff0000, v152
	v_pk_mul_f32 v[156:157], v[156:157], v[160:161]
	v_rcp_f32_e32 v152, v195
	v_pk_mul_f32 v[92:93], v[92:93], v[156:157]
	v_lshlrev_b32_e32 v156, 16, v154
	v_and_b32_e32 v157, 0xffff0000, v154
	v_pk_mul_f32 v[156:157], v[158:159], v[156:157]
	v_lshlrev_b32_e32 v158, 16, v153
	v_and_b32_e32 v159, 0xffff0000, v153
	v_rcp_f32_e32 v153, v196
	v_pk_mul_f32 v[88:89], v[88:89], v[156:157]
	v_rcp_f32_e32 v156, v162
	v_rcp_f32_e32 v157, v163
	v_lshlrev_b32_e32 v154, 16, v155
	v_and_b32_e32 v155, 0xffff0000, v155
	v_pk_mul_f32 v[152:153], v[152:153], v[154:155]
	v_pk_mul_f32 v[156:157], v[156:157], v[158:159]
	v_pk_mul_f32 v[90:91], v[90:91], v[152:153]
	v_lshlrev_b32_e32 v152, 16, v148
	v_and_b32_e32 v153, 0xffff0000, v148
	v_lshlrev_b32_e32 v154, 16, v149
	v_and_b32_e32 v155, 0xffff0000, v149
	v_rcp_f32_e32 v148, v152
	v_rcp_f32_e32 v149, v153
	v_pk_mul_f32 v[94:95], v[94:95], v[156:157]
	v_lshlrev_b32_e32 v156, 16, v150
	v_and_b32_e32 v157, 0xffff0000, v150
	v_lshlrev_b32_e32 v158, 16, v151
	v_and_b32_e32 v159, 0xffff0000, v151
	v_rcp_f32_e32 v150, v156
	v_rcp_f32_e32 v151, v157
	v_lshlrev_b32_e32 v152, 16, v144
	v_and_b32_e32 v153, 0xffff0000, v144
	v_pk_mul_f32 v[148:149], v[148:149], v[152:153]
	v_rcp_f32_e32 v144, v158
	v_pk_mul_f32 v[84:85], v[84:85], v[148:149]
	v_lshlrev_b32_e32 v148, 16, v146
	v_and_b32_e32 v149, 0xffff0000, v146
	v_pk_mul_f32 v[148:149], v[150:151], v[148:149]
	v_lshlrev_b32_e32 v150, 16, v145
	v_and_b32_e32 v151, 0xffff0000, v145
	v_rcp_f32_e32 v145, v159
	v_lshlrev_b32_e32 v146, 16, v147
	v_and_b32_e32 v147, 0xffff0000, v147
	v_pk_mul_f32 v[80:81], v[80:81], v[148:149]
	v_pk_mul_f32 v[144:145], v[144:145], v[146:147]
	v_add_co_u32_e32 v146, vcc, s73, v182
	v_rcp_f32_e32 v148, v154
	s_nop 0
	v_addc_co_u32_e32 v147, vcc, 0, v183, vcc
	v_rcp_f32_e32 v149, v155
	global_load_dwordx4 v[156:159], v[146:147], off offset:2048
	global_load_dwordx4 v[194:197], v[146:147], off offset:2304
	global_load_dwordx4 v[160:163], v[146:147], off
	global_load_dwordx4 v[198:201], v[146:147], off offset:256
	v_pk_mul_f32 v[148:149], v[148:149], v[150:151]
	v_pk_mul_f32 v[82:83], v[82:83], v[144:145]
	v_pk_mul_f32 v[86:87], v[86:87], v[148:149]
	v_lshlrev_b32_e32 v144, 16, v140
	v_and_b32_e32 v145, 0xffff0000, v140
	v_lshlrev_b32_e32 v148, 16, v141
	v_and_b32_e32 v149, 0xffff0000, v141
	v_lshlrev_b32_e32 v141, 16, v142
	v_and_b32_e32 v150, 0xffff0000, v142
	v_rcp_f32_e32 v140, v144
	v_rcp_f32_e32 v142, v141
	v_rcp_f32_e32 v141, v145
	v_lshlrev_b32_e32 v151, 16, v143
	v_and_b32_e32 v152, 0xffff0000, v143
	v_rcp_f32_e32 v143, v150
	v_lshlrev_b32_e32 v144, 16, v136
	v_and_b32_e32 v145, 0xffff0000, v136
	v_pk_mul_f32 v[140:141], v[140:141], v[144:145]
	v_rcp_f32_e32 v136, v151
	v_pk_mul_f32 v[76:77], v[76:77], v[140:141]
	v_lshlrev_b32_e32 v140, 16, v138
	v_and_b32_e32 v141, 0xffff0000, v138
; #define GAS __attribute__((address_space(1)))
; __device__ __forceinline__ float frcp(float x) { return __builtin_amdgcn_rcpf(x); }
; __device__ __forceinline__ void unpack8(u32x4 w, f32x4& a, f32x4& b) { a = (f32x4){bf_lo(w.x), bf_hi(w.x), bf_lo(w.y), bf_hi(w.y)}; b = (f32x4){bf_lo(w.z), bf_hi(w.z), bf_lo(w.w), bf_hi(w.w)}; }
;     __device__ __forceinline__ void hook(f32x4 (&acc)[2][2][4][2], const Unit& u, int seg, int wr, int wc, int fr, int fq) const {
;     ...
;                 for (int bj = 0; bj < 2; ++bj) { const GAS bf16_t* gp = gbase + (size_t)(ai * 128 + m * 16) * PW + bj * 128;
;                     ga[m][bj] = *(const GAS u32x4*)gp; gb[m][bj] = *(const GAS u32x4*)(gp + 1024); }
; #pragma unroll
;             for (int m = 0; m < 4; ++m)
; #pragma unroll
;                 for (int bj = 0; bj < 2; ++bj) { f32x4 a0, a1, b0, b1; unpack8(ga[m][bj], a0, a1); unpack8(gb[m][bj], b0, b1);
; #pragma unroll
;                     for (int i = 0; i < 4; ++i) { acc[ai][bj][m][0][i] *= a0[i] * frcp(b0[i]); acc[ai][bj][m][1][i] *= a1[i] * frcp(b1[i]); } }
	v_pk_mul_f32 v[140:141], v[142:143], v[140:141]
	v_lshlrev_b32_e32 v142, 16, v137
	v_and_b32_e32 v143, 0xffff0000, v137
	v_rcp_f32_e32 v137, v152
	v_pk_mul_f32 v[72:73], v[72:73], v[140:141]
	v_rcp_f32_e32 v140, v148
	v_rcp_f32_e32 v141, v149
	v_lshlrev_b32_e32 v138, 16, v139
	v_and_b32_e32 v139, 0xffff0000, v139
	v_pk_mul_f32 v[136:137], v[136:137], v[138:139]
	v_pk_mul_f32 v[140:141], v[140:141], v[142:143]
	v_pk_mul_f32 v[74:75], v[74:75], v[136:137]
	v_lshlrev_b32_e32 v136, 16, v132
	v_and_b32_e32 v137, 0xffff0000, v132
	v_lshlrev_b32_e32 v138, 16, v133
	v_and_b32_e32 v139, 0xffff0000, v133
	v_rcp_f32_e32 v132, v136
	v_rcp_f32_e32 v133, v137
	v_pk_mul_f32 v[78:79], v[78:79], v[140:141]
	v_lshlrev_b32_e32 v140, 16, v134
	v_and_b32_e32 v141, 0xffff0000, v134
	v_lshlrev_b32_e32 v142, 16, v135
	v_and_b32_e32 v143, 0xffff0000, v135
	v_rcp_f32_e32 v134, v140
	v_rcp_f32_e32 v135, v141
	v_lshlrev_b32_e32 v136, 16, v128
	v_and_b32_e32 v137, 0xffff0000, v128
	v_pk_mul_f32 v[132:133], v[132:133], v[136:137]
	v_rcp_f32_e32 v128, v142
	v_pk_mul_f32 v[68:69], v[68:69], v[132:133]
	v_lshlrev_b32_e32 v132, 16, v130
	v_and_b32_e32 v133, 0xffff0000, v130
	v_pk_mul_f32 v[132:133], v[134:135], v[132:133]
	v_lshlrev_b32_e32 v134, 16, v129
	v_and_b32_e32 v135, 0xffff0000, v129
	v_rcp_f32_e32 v129, v143
	v_lshlrev_b32_e32 v130, 16, v131
	v_and_b32_e32 v131, 0xffff0000, v131
	v_pk_mul_f32 v[64:65], v[64:65], v[132:133]
	v_pk_mul_f32 v[128:129], v[128:129], v[130:131]
	v_rcp_f32_e32 v132, v138
	v_pk_mul_f32 v[66:67], v[66:67], v[128:129]
	v_add_co_u32_e32 v128, vcc, s74, v182
	v_rcp_f32_e32 v133, v139
	s_nop 0
	v_addc_co_u32_e32 v129, vcc, 0, v183, vcc
	global_load_dwordx4 v[202:205], v[128:129], off
	global_load_dwordx4 v[206:209], v[128:129], off offset:256
	global_load_dwordx4 v[210:213], v[128:129], off offset:2048
	global_load_dwordx4 v[214:217], v[128:129], off offset:2304
	v_add_co_u32_e32 v128, vcc, s75, v182
	v_pk_mul_f32 v[132:133], v[132:133], v[134:135]
	s_nop 0
	v_addc_co_u32_e32 v129, vcc, 0, v183, vcc
	global_load_dwordx4 v[152:155], v[128:129], off
	global_load_dwordx4 v[144:147], v[128:129], off offset:256
	global_load_dwordx4 v[218:221], v[128:129], off offset:2048
	global_load_dwordx4 v[148:151], v[128:129], off offset:2304
	s_waitcnt vmcnt(0)
	v_lshlrev_b32_e32 v193, 16, v156
	v_and_b32_e32 v222, 0xffff0000, v156
	v_lshlrev_b32_e32 v224, 16, v157
	v_and_b32_e32 v225, 0xffff0000, v157
	v_rcp_f32_e32 v156, v193
	v_rcp_f32_e32 v157, v222
	v_lshlrev_b32_e32 v223, 16, v158
	v_and_b32_e32 v226, 0xffff0000, v158
	v_pk_mul_f32 v[70:71], v[70:71], v[132:133]
	v_add_co_u32_e32 v132, vcc, s76, v182
	v_lshlrev_b32_e32 v227, 16, v159
	v_and_b32_e32 v228, 0xffff0000, v159
	v_rcp_f32_e32 v158, v223
	v_rcp_f32_e32 v159, v226
	v_addc_co_u32_e32 v133, vcc, 0, v183, vcc
	v_lshlrev_b32_e32 v222, 16, v160
	v_and_b32_e32 v223, 0xffff0000, v160
	global_load_dwordx4 v[136:139], v[132:133], off
	global_load_dwordx4 v[128:131], v[132:133], off offset:256
	global_load_dwordx4 v[140:143], v[132:133], off offset:2048
	s_nop 0
	global_load_dwordx4 v[132:135], v[132:133], off offset:2304
	v_pk_mul_f32 v[156:157], v[156:157], v[222:223]
	v_lshlrev_b32_e32 v160, 16, v161
	v_pk_mul_f32 v[60:61], v[60:61], v[156:157]
	v_lshlrev_b32_e32 v156, 16, v162
	v_and_b32_e32 v157, 0xffff0000, v162
	v_pk_mul_f32 v[156:157], v[158:159], v[156:157]
	v_rcp_f32_e32 v158, v227
	v_pk_mul_f32 v[56:57], v[56:57], v[156:157]
	v_rcp_f32_e32 v156, v224
	v_rcp_f32_e32 v157, v225
	v_rcp_f32_e32 v159, v228
	v_and_b32_e32 v161, 0xffff0000, v161
	v_lshlrev_b32_e32 v162, 16, v195
	v_pk_mul_f32 v[156:157], v[156:157], v[160:161]
	v_lshlrev_b32_e32 v160, 16, v198
	v_pk_mul_f32 v[62:63], v[62:63], v[156:157]
	v_lshlrev_b32_e32 v156, 16, v163
	v_and_b32_e32 v157, 0xffff0000, v163
	v_pk_mul_f32 v[156:157], v[158:159], v[156:157]
	v_lshlrev_b32_e32 v158, 16, v196
	v_pk_mul_f32 v[58:59], v[58:59], v[156:157]
	v_lshlrev_b32_e32 v156, 16, v194
	v_and_b32_e32 v157, 0xffff0000, v194
	v_rcp_f32_e32 v156, v156
	v_rcp_f32_e32 v157, v157
	v_and_b32_e32 v159, 0xffff0000, v196
	v_rcp_f32_e32 v158, v158
	v_rcp_f32_e32 v159, v159
	v_and_b32_e32 v161, 0xffff0000, v198
	v_pk_mul_f32 v[156:157], v[156:157], v[160:161]
	v_and_b32_e32 v163, 0xffff0000, v195
	v_pk_mul_f32 v[52:53], v[52:53], v[156:157]
	v_lshlrev_b32_e32 v156, 16, v200
	v_and_b32_e32 v157, 0xffff0000, v200
	v_pk_mul_f32 v[156:157], v[158:159], v[156:157]
	v_lshlrev_b32_e32 v193, 16, v197
	v_pk_mul_f32 v[48:49], v[48:49], v[156:157]
	v_rcp_f32_e32 v156, v162
	v_rcp_f32_e32 v157, v163
	v_and_b32_e32 v194, 0xffff0000, v197
	v_rcp_f32_e32 v158, v193
	v_rcp_f32_e32 v159, v194
	v_lshlrev_b32_e32 v160, 16, v199
	v_and_b32_e32 v161, 0xffff0000, v199
	v_pk_mul_f32 v[156:157], v[156:157], v[160:161]
	s_waitcnt vmcnt(0)
; #define GAS __attribute__((address_space(1)))
; __device__ __forceinline__ float frcp(float x) { return __builtin_amdgcn_rcpf(x); }
; __device__ __forceinline__ void unpack8(u32x4 w, f32x4& a, f32x4& b) { a = (f32x4){bf_lo(w.x), bf_hi(w.x), bf_lo(w.y), bf_hi(w.y)}; b = (f32x4){bf_lo(w.z), bf_hi(w.z), bf_lo(w.w), bf_hi(w.w)}; }
;     __device__ __forceinline__ void hook(f32x4 (&acc)[2][2][4][2], const Unit& u, int seg, int wr, int wc, int fr, int fq) const {
;     ...
;                 for (int bj = 0; bj < 2; ++bj) { const GAS bf16_t* gp = gbase + (size_t)(ai * 128 + m * 16) * PW + bj * 128;
;                     ga[m][bj] = *(const GAS u32x4*)gp; gb[m][bj] = *(const GAS u32x4*)(gp + 1024); }
; #pragma unroll
;             for (int m = 0; m < 4; ++m)
; #pragma unroll
;                 for (int bj = 0; bj < 2; ++bj) { f32x4 a0, a1, b0, b1; unpack8(ga[m][bj], a0, a1); unpack8(gb[m][bj], b0, b1);
; #pragma unroll
;                     for (int i = 0; i < 4; ++i) { acc[ai][bj][m][0][i] *= a0[i] * frcp(b0[i]); acc[ai][bj][m][1][i] *= a1[i] * frcp(b1[i]); } }
	v_lshlrev_b32_e32 v160, 16, v202
	v_pk_mul_f32 v[54:55], v[54:55], v[156:157]
	v_lshlrev_b32_e32 v156, 16, v201
	v_and_b32_e32 v157, 0xffff0000, v201
	v_pk_mul_f32 v[156:157], v[158:159], v[156:157]
	v_lshlrev_b32_e32 v158, 16, v212
	v_pk_mul_f32 v[50:51], v[50:51], v[156:157]
	v_lshlrev_b32_e32 v156, 16, v210
	v_and_b32_e32 v157, 0xffff0000, v210
	v_rcp_f32_e32 v156, v156
	v_rcp_f32_e32 v157, v157
	v_and_b32_e32 v159, 0xffff0000, v212
	v_rcp_f32_e32 v158, v158
	v_rcp_f32_e32 v159, v159
	v_and_b32_e32 v161, 0xffff0000, v202
	v_pk_mul_f32 v[156:157], v[156:157], v[160:161]
	v_lshlrev_b32_e32 v162, 16, v211
	v_pk_mul_f32 v[44:45], v[44:45], v[156:157]
	v_lshlrev_b32_e32 v156, 16, v204
	v_and_b32_e32 v157, 0xffff0000, v204
	v_and_b32_e32 v163, 0xffff0000, v211
	v_pk_mul_f32 v[156:157], v[158:159], v[156:157]
	v_lshlrev_b32_e32 v193, 16, v213
	v_pk_mul_f32 v[40:41], v[40:41], v[156:157]
	v_rcp_f32_e32 v156, v162
	v_rcp_f32_e32 v157, v163
	v_and_b32_e32 v194, 0xffff0000, v213
	v_rcp_f32_e32 v158, v193
	v_rcp_f32_e32 v159, v194
	v_lshlrev_b32_e32 v160, 16, v203
	v_and_b32_e32 v161, 0xffff0000, v203
	v_pk_mul_f32 v[156:157], v[156:157], v[160:161]
	v_lshlrev_b32_e32 v160, 16, v206
	v_pk_mul_f32 v[46:47], v[46:47], v[156:157]
	v_lshlrev_b32_e32 v156, 16, v205
	v_and_b32_e32 v157, 0xffff0000, v205
	v_pk_mul_f32 v[156:157], v[158:159], v[156:157]
	v_lshlrev_b32_e32 v158, 16, v216
	v_pk_mul_f32 v[42:43], v[42:43], v[156:157]
	v_lshlrev_b32_e32 v156, 16, v214
	v_and_b32_e32 v157, 0xffff0000, v214
	v_rcp_f32_e32 v156, v156
	v_rcp_f32_e32 v157, v157
	v_and_b32_e32 v159, 0xffff0000, v216
	v_rcp_f32_e32 v158, v158
	v_rcp_f32_e32 v159, v159
	v_and_b32_e32 v161, 0xffff0000, v206
	v_pk_mul_f32 v[156:157], v[156:157], v[160:161]
	v_lshlrev_b32_e32 v162, 16, v215
	v_pk_mul_f32 v[36:37], v[36:37], v[156:157]
	v_lshlrev_b32_e32 v156, 16, v208
	v_and_b32_e32 v157, 0xffff0000, v208
	v_and_b32_e32 v163, 0xffff0000, v215
	v_pk_mul_f32 v[156:157], v[158:159], v[156:157]
	v_lshlrev_b32_e32 v193, 16, v217
	v_pk_mul_f32 v[32:33], v[32:33], v[156:157]
	v_rcp_f32_e32 v156, v162
	v_rcp_f32_e32 v157, v163
	v_and_b32_e32 v194, 0xffff0000, v217
	v_rcp_f32_e32 v158, v193
	v_rcp_f32_e32 v159, v194
	v_lshlrev_b32_e32 v160, 16, v207
	v_and_b32_e32 v161, 0xffff0000, v207
	v_pk_mul_f32 v[156:157], v[156:157], v[160:161]
	v_lshlrev_b32_e32 v160, 16, v152
	v_pk_mul_f32 v[38:39], v[38:39], v[156:157]
	v_lshlrev_b32_e32 v156, 16, v209
	v_and_b32_e32 v157, 0xffff0000, v209
	v_pk_mul_f32 v[156:157], v[158:159], v[156:157]
	v_lshlrev_b32_e32 v158, 16, v220
	v_pk_mul_f32 v[34:35], v[34:35], v[156:157]
	v_lshlrev_b32_e32 v156, 16, v218
	v_and_b32_e32 v157, 0xffff0000, v218
	v_rcp_f32_e32 v156, v156
	v_rcp_f32_e32 v157, v157
	v_and_b32_e32 v159, 0xffff0000, v220
	v_rcp_f32_e32 v158, v158
	v_rcp_f32_e32 v159, v159
	v_and_b32_e32 v161, 0xffff0000, v152
	v_pk_mul_f32 v[156:157], v[156:157], v[160:161]
	v_lshlrev_b32_e32 v193, 16, v221
	v_and_b32_e32 v194, 0xffff0000, v221
	v_pk_mul_f32 v[28:29], v[28:29], v[156:157]
	v_lshlrev_b32_e32 v156, 16, v154
	v_and_b32_e32 v157, 0xffff0000, v154
	v_pk_mul_f32 v[156:157], v[158:159], v[156:157]
	v_rcp_f32_e32 v152, v193
	v_lshlrev_b32_e32 v158, 16, v153
	v_and_b32_e32 v159, 0xffff0000, v153
	v_rcp_f32_e32 v153, v194
	v_lshlrev_b32_e32 v162, 16, v219
	v_and_b32_e32 v163, 0xffff0000, v219
	v_pk_mul_f32 v[24:25], v[24:25], v[156:157]
	v_rcp_f32_e32 v156, v162
	v_rcp_f32_e32 v157, v163
	v_lshlrev_b32_e32 v154, 16, v155
	v_and_b32_e32 v155, 0xffff0000, v155
	v_pk_mul_f32 v[152:153], v[152:153], v[154:155]
	v_pk_mul_f32 v[156:157], v[156:157], v[158:159]
	v_pk_mul_f32 v[26:27], v[26:27], v[152:153]
	v_lshlrev_b32_e32 v152, 16, v148
	v_and_b32_e32 v153, 0xffff0000, v148
	v_lshlrev_b32_e32 v154, 16, v149
	v_and_b32_e32 v155, 0xffff0000, v149
	v_rcp_f32_e32 v148, v152
	v_rcp_f32_e32 v149, v153
	v_pk_mul_f32 v[30:31], v[30:31], v[156:157]
	v_lshlrev_b32_e32 v156, 16, v150
	v_and_b32_e32 v157, 0xffff0000, v150
	v_lshlrev_b32_e32 v158, 16, v151
	v_and_b32_e32 v159, 0xffff0000, v151
	v_rcp_f32_e32 v150, v156
	v_rcp_f32_e32 v151, v157
	v_lshlrev_b32_e32 v152, 16, v144
	v_and_b32_e32 v153, 0xffff0000, v144
	v_pk_mul_f32 v[148:149], v[148:149], v[152:153]
	v_rcp_f32_e32 v144, v158
	v_pk_mul_f32 v[20:21], v[20:21], v[148:149]
	v_lshlrev_b32_e32 v148, 16, v146
	v_and_b32_e32 v149, 0xffff0000, v146
	v_pk_mul_f32 v[148:149], v[150:151], v[148:149]
	v_lshlrev_b32_e32 v150, 16, v145
	v_and_b32_e32 v151, 0xffff0000, v145
	v_rcp_f32_e32 v145, v159
	v_pk_mul_f32 v[16:17], v[16:17], v[148:149]
	v_rcp_f32_e32 v148, v154
	v_rcp_f32_e32 v149, v155
	v_lshlrev_b32_e32 v146, 16, v147
	v_and_b32_e32 v147, 0xffff0000, v147
	v_pk_mul_f32 v[144:145], v[144:145], v[146:147]
	v_pk_mul_f32 v[148:149], v[148:149], v[150:151]
	v_pk_mul_f32 v[18:19], v[18:19], v[144:145]
	s_waitcnt vmcnt(0)
; #define GAS __attribute__((address_space(1)))
; __device__ __forceinline__ float frcp(float x) { return __builtin_amdgcn_rcpf(x); }
; __device__ __forceinline__ void unpack8(u32x4 w, f32x4& a, f32x4& b) { a = (f32x4){bf_lo(w.x), bf_hi(w.x), bf_lo(w.y), bf_hi(w.y)}; b = (f32x4){bf_lo(w.z), bf_hi(w.z), bf_lo(w.w), bf_hi(w.w)}; }
;     __device__ __forceinline__ void hook(f32x4 (&acc)[2][2][4][2], const Unit& u, int seg, int wr, int wc, int fr, int fq) const {
;     ...
;                 for (int bj = 0; bj < 2; ++bj) { const GAS bf16_t* gp = gbase + (size_t)(ai * 128 + m * 16) * PW + bj * 128;
;                     ga[m][bj] = *(const GAS u32x4*)gp; gb[m][bj] = *(const GAS u32x4*)(gp + 1024); }
; #pragma unroll
;             for (int m = 0; m < 4; ++m)
; #pragma unroll
;                 for (int bj = 0; bj < 2; ++bj) { f32x4 a0, a1, b0, b1; unpack8(ga[m][bj], a0, a1); unpack8(gb[m][bj], b0, b1);
; #pragma unroll
;                     for (int i = 0; i < 4; ++i) { acc[ai][bj][m][0][i] *= a0[i] * frcp(b0[i]); acc[ai][bj][m][1][i] *= a1[i] * frcp(b1[i]); } }
	v_lshlrev_b32_e32 v144, 16, v140
	v_and_b32_e32 v145, 0xffff0000, v140
	v_lshlrev_b32_e32 v146, 16, v141
	v_and_b32_e32 v147, 0xffff0000, v141
	v_rcp_f32_e32 v140, v144
	v_rcp_f32_e32 v141, v145
	v_pk_mul_f32 v[22:23], v[22:23], v[148:149]
	v_lshlrev_b32_e32 v148, 16, v142
	v_and_b32_e32 v149, 0xffff0000, v142
	v_lshlrev_b32_e32 v150, 16, v143
	v_and_b32_e32 v151, 0xffff0000, v143
	v_rcp_f32_e32 v142, v148
	v_rcp_f32_e32 v143, v149
	v_lshlrev_b32_e32 v144, 16, v136
	v_and_b32_e32 v145, 0xffff0000, v136
	v_pk_mul_f32 v[140:141], v[140:141], v[144:145]
	v_rcp_f32_e32 v136, v150
	v_pk_mul_f32 v[12:13], v[12:13], v[140:141]
	v_lshlrev_b32_e32 v140, 16, v138
	v_and_b32_e32 v141, 0xffff0000, v138
	v_pk_mul_f32 v[140:141], v[142:143], v[140:141]
	v_lshlrev_b32_e32 v142, 16, v137
	v_and_b32_e32 v143, 0xffff0000, v137
	v_rcp_f32_e32 v137, v151
	v_pk_mul_f32 v[8:9], v[8:9], v[140:141]
	v_rcp_f32_e32 v140, v146
	v_rcp_f32_e32 v141, v147
	v_lshlrev_b32_e32 v138, 16, v139
	v_and_b32_e32 v139, 0xffff0000, v139
	v_pk_mul_f32 v[136:137], v[136:137], v[138:139]
	v_pk_mul_f32 v[140:141], v[140:141], v[142:143]
	v_pk_mul_f32 v[10:11], v[10:11], v[136:137]
	v_lshlrev_b32_e32 v136, 16, v132
	v_and_b32_e32 v137, 0xffff0000, v132
	v_lshlrev_b32_e32 v138, 16, v133
	v_and_b32_e32 v139, 0xffff0000, v133
	v_rcp_f32_e32 v132, v136
	v_rcp_f32_e32 v133, v137
	v_pk_mul_f32 v[14:15], v[14:15], v[140:141]
	v_lshlrev_b32_e32 v140, 16, v134
	v_and_b32_e32 v141, 0xffff0000, v134
	v_lshlrev_b32_e32 v142, 16, v135
	v_and_b32_e32 v143, 0xffff0000, v135
	v_rcp_f32_e32 v134, v140
	v_rcp_f32_e32 v135, v141
	v_lshlrev_b32_e32 v136, 16, v128
	v_and_b32_e32 v137, 0xffff0000, v128
	v_pk_mul_f32 v[132:133], v[132:133], v[136:137]
	v_rcp_f32_e32 v128, v142
	v_pk_mul_f32 v[4:5], v[4:5], v[132:133]
	v_lshlrev_b32_e32 v132, 16, v130
	v_and_b32_e32 v133, 0xffff0000, v130
	v_pk_mul_f32 v[132:133], v[134:135], v[132:133]
	v_lshlrev_b32_e32 v134, 16, v129
	v_pk_mul_f32 v[0:1], v[0:1], v[132:133]
	v_rcp_f32_e32 v132, v138
	v_rcp_f32_e32 v133, v139
	v_and_b32_e32 v135, 0xffff0000, v129
	v_rcp_f32_e32 v129, v143
	v_lshlrev_b32_e32 v130, 16, v131
	v_and_b32_e32 v131, 0xffff0000, v131
	v_pk_mul_f32 v[132:133], v[132:133], v[134:135]
	v_pk_mul_f32 v[128:129], v[128:129], v[130:131]
	v_pk_mul_f32 v[6:7], v[6:7], v[132:133]
	v_pk_mul_f32 v[2:3], v[2:3], v[128:129]

; #define GAS __attribute__((address_space(1)))
; __device__ __forceinline__ u32x4 pack8(f32x4 a, f32x4 b) { u32x4 w; w.x = pk2(a[0], a[1]); w.y = pk2(a[2], a[3]); w.z = pk2(b[0], b[1]); w.w = pk2(b[2], b[3]); return w; }
; __device__ __forceinline__ void unpack8(u32x4 w, f32x4& a, f32x4& b) { a = (f32x4){bf_lo(w.x), bf_hi(w.x), bf_lo(w.y), bf_hi(w.y)}; b = (f32x4){bf_lo(w.z), bf_hi(w.z), bf_lo(w.w), bf_hi(w.w)}; }
;     __device__ __forceinline__ void operator()(const f32x4 (&acc)[2][2][4][2], const Unit& u, int wr, int wc, int fr, int fq) const {
; #pragma unroll
;         for (int ai = 0; ai < 2; ++ai)
; #pragma unroll
;             for (int m = 0; m < 4; ++m) {
;                 const int row = u.pm * 256 + ai * 128 + wr * 64 + m * 16 + fr;
; #pragma unroll
;                 for (int bj = 0; bj < 2; ++bj) {
;                     const int c = u.pn * 256 + bj * 128 + wc * 32 + 8 * fq;
;                     f32x4 g0, g1; unpack8(*(const GAS u32x4*)(Pg + (size_t)row * PW + PC_GATE + 2048 + c), g0, g1);
;                     *(GAS u32x4*)(Mgp + (size_t)row * 1024 + c) = pack8(acc[ai][bj][m][0] * g0, acc[ai][bj][m][1] * g1);
;                 }
;             }
;     }
.LBB0_1034:
	v_lshl_add_u32 v130, s87, 8, v188
	v_lshl_add_u32 v134, s88, 8, v190
	v_mov_b64_e32 v[132:133], s[8:9]
	v_mad_i64_i32 v[128:129], s[50:51], v130, s70, v[132:133]
	v_ashrrev_i32_e32 v135, 31, v134
	v_lshl_add_u64 v[140:141], v[128:129], 0, s[40:41]
	v_lshlrev_b64 v[128:129], 1, v[134:135]
	v_lshl_add_u64 v[136:137], v[140:141], 0, v[128:129]
	s_mov_b32 s98, 0x28000
	s_mov_b32 s99, 0
	s_mov_b32 s100, 0xc8000
	s_mov_b32 s101, 0
	global_load_dword v246, v[136:137], off offset:256
	v_lshl_add_u64 v[242:243], v[136:137], 0, s[98:99]
	global_load_dword v246, v[242:243], off
	global_load_dword v246, v[242:243], off offset:256
	v_lshl_add_u64 v[242:243], v[242:243], 0, s[98:99]
	global_load_dword v246, v[242:243], off
	global_load_dword v246, v[242:243], off offset:256
	v_lshl_add_u64 v[242:243], v[242:243], 0, s[98:99]
	global_load_dword v246, v[242:243], off
	global_load_dword v246, v[242:243], off offset:256
	v_lshl_add_u64 v[242:243], v[242:243], 0, s[100:101]
	global_load_dword v246, v[242:243], off
	global_load_dword v246, v[242:243], off offset:256
	v_lshl_add_u64 v[242:243], v[242:243], 0, s[98:99]
	global_load_dword v246, v[242:243], off
	global_load_dword v246, v[242:243], off offset:256
	v_lshl_add_u64 v[242:243], v[242:243], 0, s[98:99]
	global_load_dword v246, v[242:243], off
	global_load_dword v246, v[242:243], off offset:256
	v_lshl_add_u64 v[242:243], v[242:243], 0, s[98:99]
	global_load_dword v246, v[242:243], off
	global_load_dword v246, v[242:243], off offset:256
	global_load_dwordx4 v[136:139], v[136:137], off
	v_ashrrev_i32_e32 v131, 31, v130
	v_add_u32_e32 v134, 0x80, v134
	v_lshlrev_b64 v[142:143], 11, v[130:131]
	v_ashrrev_i32_e32 v135, 31, v134
	v_lshl_add_u64 v[142:143], s[28:29], 0, v[142:143]
	v_lshlrev_b64 v[134:135], 1, v[134:135]
	v_lshl_add_u64 v[142:143], v[142:143], 0, v[128:129]
	v_lshl_add_u64 v[140:141], v[140:141], 0, v[134:135]
	s_andn2_b64 vcc, exec, s[4:5]
	s_mov_b64 s[4:5], -1
	s_waitcnt vmcnt(0)
	v_lshlrev_b32_e32 v144, 16, v136
	v_and_b32_e32 v145, 0xffff0000, v136
	v_lshlrev_b32_e32 v136, 16, v137
	v_and_b32_e32 v137, 0xffff0000, v137
	v_lshlrev_b32_e32 v146, 16, v138
	v_and_b32_e32 v147, 0xffff0000, v138
	v_lshlrev_b32_e32 v138, 16, v139
	v_and_b32_e32 v139, 0xffff0000, v139
	v_pk_mul_f32 v[122:123], v[122:123], v[136:137]
	v_pk_mul_f32 v[120:121], v[120:121], v[144:145]
	v_pk_mul_f32 v[124:125], v[124:125], v[146:147]
	v_or_b32_e32 v136, 16, v130
	v_pk_mul_f32 v[126:127], v[126:127], v[138:139]
	v_cvt_pk_bf16_f32 v120, v120, v121
	v_cvt_pk_bf16_f32 v121, v122, v123
	v_cvt_pk_bf16_f32 v122, v124, v125
	v_mad_i64_i32 v[124:125], s[50:51], v136, s70, v[132:133]
	v_cvt_pk_bf16_f32 v123, v126, v127
	v_lshl_add_u64 v[138:139], v[124:125], 0, s[40:41]
	global_store_dwordx4 v[142:143], v[120:123], off
	v_lshl_add_u64 v[124:125], v[138:139], 0, v[128:129]
	global_load_dwordx4 v[120:123], v[140:141], off
	v_ashrrev_i32_e32 v137, 31, v136
	global_load_dwordx4 v[124:127], v[124:125], off
	v_lshlrev_b64 v[136:137], 11, v[136:137]
	v_lshl_add_u64 v[136:137], s[28:29], 0, v[136:137]
	v_lshl_add_u64 v[136:137], v[136:137], 0, v[128:129]
	v_lshl_add_u64 v[138:139], v[138:139], 0, v[134:135]
	s_waitcnt vmcnt(0)
	v_lshlrev_b32_e32 v140, 16, v120
	v_and_b32_e32 v141, 0xffff0000, v120
	v_lshlrev_b32_e32 v120, 16, v121
	v_and_b32_e32 v121, 0xffff0000, v121
	v_lshlrev_b32_e32 v144, 16, v122
	v_and_b32_e32 v145, 0xffff0000, v122
	v_lshlrev_b32_e32 v122, 16, v123
	v_and_b32_e32 v123, 0xffff0000, v123
	v_lshlrev_b32_e32 v146, 16, v124
	v_and_b32_e32 v147, 0xffff0000, v124
	v_lshlrev_b32_e32 v124, 16, v125
	v_and_b32_e32 v125, 0xffff0000, v125
	v_lshlrev_b32_e32 v148, 16, v126
	v_and_b32_e32 v149, 0xffff0000, v126
	v_lshlrev_b32_e32 v126, 16, v127
	v_and_b32_e32 v127, 0xffff0000, v127
	v_pk_mul_f32 v[118:119], v[118:119], v[120:121]
	v_pk_mul_f32 v[116:117], v[116:117], v[140:141]
	v_pk_mul_f32 v[114:115], v[114:115], v[122:123]
	v_pk_mul_f32 v[112:113], v[112:113], v[144:145]
	v_pk_mul_f32 v[110:111], v[110:111], v[124:125]
	v_pk_mul_f32 v[108:109], v[108:109], v[146:147]
	v_pk_mul_f32 v[120:121], v[106:107], v[126:127]
	v_pk_mul_f32 v[122:123], v[104:105], v[148:149]
	v_cvt_pk_bf16_f32 v104, v116, v117
	v_cvt_pk_bf16_f32 v105, v118, v119
	v_cvt_pk_bf16_f32 v106, v112, v113
	v_cvt_pk_bf16_f32 v107, v114, v115
	v_cvt_pk_bf16_f32 v108, v108, v109
	v_cvt_pk_bf16_f32 v109, v110, v111
	v_or_b32_e32 v112, 32, v130
	v_cvt_pk_bf16_f32 v110, v122, v123
	v_cvt_pk_bf16_f32 v111, v120, v121
	global_store_dwordx4 v[142:143], v[104:107], off offset:256
	global_store_dwordx4 v[136:137], v[108:111], off
	global_load_dwordx4 v[104:107], v[138:139], off
	v_ashrrev_i32_e32 v113, 31, v112
	v_mad_i64_i32 v[108:109], s[50:51], v112, s70, v[132:133]
	v_lshl_add_u64 v[114:115], v[108:109], 0, s[40:41]
	v_lshl_add_u64 v[108:109], v[114:115], 0, v[128:129]
	global_load_dwordx4 v[108:111], v[108:109], off
	v_lshlrev_b64 v[112:113], 11, v[112:113]
	v_lshl_add_u64 v[112:113], s[28:29], 0, v[112:113]
	v_lshl_add_u64 v[112:113], v[112:113], 0, v[128:129]
	v_lshl_add_u64 v[114:115], v[114:115], 0, v[134:135]
	s_waitcnt vmcnt(0)
; #define GAS __attribute__((address_space(1)))
; __device__ __forceinline__ u32x4 pack8(f32x4 a, f32x4 b) { u32x4 w; w.x = pk2(a[0], a[1]); w.y = pk2(a[2], a[3]); w.z = pk2(b[0], b[1]); w.w = pk2(b[2], b[3]); return w; }
; __device__ __forceinline__ void unpack8(u32x4 w, f32x4& a, f32x4& b) { a = (f32x4){bf_lo(w.x), bf_hi(w.x), bf_lo(w.y), bf_hi(w.y)}; b = (f32x4){bf_lo(w.z), bf_hi(w.z), bf_lo(w.w), bf_hi(w.w)}; }
;     __device__ __forceinline__ void operator()(const f32x4 (&acc)[2][2][4][2], const Unit& u, int wr, int wc, int fr, int fq) const {
;     ...
;             for (int m = 0; m < 4; ++m) {
;                 const int row = u.pm * 256 + ai * 128 + wr * 64 + m * 16 + fr;
; #pragma unroll
;                 for (int bj = 0; bj < 2; ++bj) {
;                     const int c = u.pn * 256 + bj * 128 + wc * 32 + 8 * fq;
;                     f32x4 g0, g1; unpack8(*(const GAS u32x4*)(Pg + (size_t)row * PW + PC_GATE + 2048 + c), g0, g1);
;                     *(GAS u32x4*)(Mgp + (size_t)row * 1024 + c) = pack8(acc[ai][bj][m][0] * g0, acc[ai][bj][m][1] * g1);
;                 }
;             }
	v_lshlrev_b32_e32 v116, 16, v104
	v_and_b32_e32 v117, 0xffff0000, v104
	v_lshlrev_b32_e32 v104, 16, v105
	v_and_b32_e32 v105, 0xffff0000, v105
	v_lshlrev_b32_e32 v118, 16, v106
	v_and_b32_e32 v119, 0xffff0000, v106
	v_lshlrev_b32_e32 v106, 16, v107
	v_and_b32_e32 v107, 0xffff0000, v107
	v_lshlrev_b32_e32 v120, 16, v108
	v_and_b32_e32 v121, 0xffff0000, v108
	v_lshlrev_b32_e32 v108, 16, v109
	v_and_b32_e32 v109, 0xffff0000, v109
	v_lshlrev_b32_e32 v122, 16, v110
	v_and_b32_e32 v123, 0xffff0000, v110
	v_lshlrev_b32_e32 v110, 16, v111
	v_and_b32_e32 v111, 0xffff0000, v111
	v_pk_mul_f32 v[102:103], v[102:103], v[104:105]
	v_pk_mul_f32 v[100:101], v[100:101], v[116:117]
	v_pk_mul_f32 v[98:99], v[98:99], v[106:107]
	v_pk_mul_f32 v[96:97], v[96:97], v[118:119]
	v_pk_mul_f32 v[94:95], v[94:95], v[108:109]
	v_pk_mul_f32 v[92:93], v[92:93], v[120:121]
	v_pk_mul_f32 v[104:105], v[90:91], v[110:111]
	v_pk_mul_f32 v[106:107], v[88:89], v[122:123]
	v_cvt_pk_bf16_f32 v88, v100, v101
	v_cvt_pk_bf16_f32 v89, v102, v103
	v_cvt_pk_bf16_f32 v90, v96, v97
	v_cvt_pk_bf16_f32 v91, v98, v99
	v_cvt_pk_bf16_f32 v92, v92, v93
	v_cvt_pk_bf16_f32 v93, v94, v95
	v_or_b32_e32 v96, 48, v130
	v_cvt_pk_bf16_f32 v94, v106, v107
	v_cvt_pk_bf16_f32 v95, v104, v105
	global_store_dwordx4 v[136:137], v[88:91], off offset:256
	global_store_dwordx4 v[112:113], v[92:95], off
	global_load_dwordx4 v[88:91], v[114:115], off
	v_ashrrev_i32_e32 v97, 31, v96
	v_mad_i64_i32 v[92:93], s[50:51], v96, s70, v[132:133]
	v_lshl_add_u64 v[98:99], v[92:93], 0, s[40:41]
	v_lshl_add_u64 v[92:93], v[98:99], 0, v[128:129]
	global_load_dwordx4 v[92:95], v[92:93], off
	v_lshlrev_b64 v[96:97], 11, v[96:97]
	v_lshl_add_u64 v[96:97], s[28:29], 0, v[96:97]
	v_lshl_add_u64 v[96:97], v[96:97], 0, v[128:129]
	v_lshl_add_u64 v[98:99], v[98:99], 0, v[134:135]
	s_waitcnt vmcnt(0)
	v_lshlrev_b32_e32 v100, 16, v88
	v_and_b32_e32 v101, 0xffff0000, v88
	v_lshlrev_b32_e32 v88, 16, v89
	v_and_b32_e32 v89, 0xffff0000, v89
	v_lshlrev_b32_e32 v102, 16, v90
	v_and_b32_e32 v103, 0xffff0000, v90
	v_lshlrev_b32_e32 v90, 16, v91
	v_and_b32_e32 v91, 0xffff0000, v91
	v_lshlrev_b32_e32 v104, 16, v92
	v_and_b32_e32 v105, 0xffff0000, v92
	v_lshlrev_b32_e32 v92, 16, v93
	v_and_b32_e32 v93, 0xffff0000, v93
	v_lshlrev_b32_e32 v106, 16, v94
	v_and_b32_e32 v107, 0xffff0000, v94
	v_lshlrev_b32_e32 v94, 16, v95
	v_and_b32_e32 v95, 0xffff0000, v95
	v_pk_mul_f32 v[86:87], v[86:87], v[88:89]
	v_pk_mul_f32 v[84:85], v[84:85], v[100:101]
	v_pk_mul_f32 v[82:83], v[82:83], v[90:91]
	v_pk_mul_f32 v[80:81], v[80:81], v[102:103]
	v_pk_mul_f32 v[78:79], v[78:79], v[92:93]
	v_pk_mul_f32 v[76:77], v[76:77], v[104:105]
	v_pk_mul_f32 v[88:89], v[74:75], v[94:95]
	v_pk_mul_f32 v[90:91], v[72:73], v[106:107]
	v_cvt_pk_bf16_f32 v72, v84, v85
	v_cvt_pk_bf16_f32 v73, v86, v87
	v_cvt_pk_bf16_f32 v74, v80, v81
	v_cvt_pk_bf16_f32 v75, v82, v83
	v_cvt_pk_bf16_f32 v76, v76, v77
	v_cvt_pk_bf16_f32 v77, v78, v79
	v_add_u32_e32 v80, 0x80, v130
	v_cvt_pk_bf16_f32 v78, v90, v91
	v_cvt_pk_bf16_f32 v79, v88, v89
	global_store_dwordx4 v[112:113], v[72:75], off offset:256
	global_store_dwordx4 v[96:97], v[76:79], off
	global_load_dwordx4 v[72:75], v[98:99], off
	v_ashrrev_i32_e32 v81, 31, v80
	v_mad_i64_i32 v[76:77], s[50:51], v80, s70, v[132:133]
	v_lshl_add_u64 v[82:83], v[76:77], 0, s[40:41]
	v_lshl_add_u64 v[76:77], v[82:83], 0, v[128:129]
	global_load_dwordx4 v[76:79], v[76:77], off
	v_lshlrev_b64 v[80:81], 11, v[80:81]
	v_lshl_add_u64 v[80:81], s[28:29], 0, v[80:81]
	v_lshl_add_u64 v[80:81], v[80:81], 0, v[128:129]
	v_lshl_add_u64 v[82:83], v[82:83], 0, v[134:135]
	s_waitcnt vmcnt(0)
	v_lshlrev_b32_e32 v84, 16, v72
	v_and_b32_e32 v85, 0xffff0000, v72
	v_lshlrev_b32_e32 v72, 16, v73
	v_and_b32_e32 v73, 0xffff0000, v73
	v_lshlrev_b32_e32 v86, 16, v74
	v_and_b32_e32 v87, 0xffff0000, v74
	v_lshlrev_b32_e32 v74, 16, v75
	v_and_b32_e32 v75, 0xffff0000, v75
	v_lshlrev_b32_e32 v88, 16, v76
	v_and_b32_e32 v89, 0xffff0000, v76
	v_lshlrev_b32_e32 v76, 16, v77
	v_and_b32_e32 v77, 0xffff0000, v77
	v_lshlrev_b32_e32 v90, 16, v78
	v_and_b32_e32 v91, 0xffff0000, v78
	v_lshlrev_b32_e32 v78, 16, v79
	v_and_b32_e32 v79, 0xffff0000, v79
	v_pk_mul_f32 v[70:71], v[70:71], v[72:73]
	v_pk_mul_f32 v[68:69], v[68:69], v[84:85]
	v_pk_mul_f32 v[66:67], v[66:67], v[74:75]
	v_pk_mul_f32 v[64:65], v[64:65], v[86:87]
	v_pk_mul_f32 v[62:63], v[62:63], v[76:77]
	v_pk_mul_f32 v[60:61], v[60:61], v[88:89]
	v_pk_mul_f32 v[72:73], v[58:59], v[78:79]
	v_pk_mul_f32 v[74:75], v[56:57], v[90:91]
	v_cvt_pk_bf16_f32 v56, v68, v69
	v_cvt_pk_bf16_f32 v57, v70, v71
	v_cvt_pk_bf16_f32 v58, v64, v65
	v_cvt_pk_bf16_f32 v59, v66, v67
	v_cvt_pk_bf16_f32 v60, v60, v61
	v_cvt_pk_bf16_f32 v61, v62, v63
	v_add_u32_e32 v64, 0x90, v130
	v_cvt_pk_bf16_f32 v62, v74, v75
	v_cvt_pk_bf16_f32 v63, v72, v73
	global_store_dwordx4 v[96:97], v[56:59], off offset:256
	global_store_dwordx4 v[80:81], v[60:63], off
	global_load_dwordx4 v[56:59], v[82:83], off
	v_ashrrev_i32_e32 v65, 31, v64
	v_mad_i64_i32 v[60:61], s[50:51], v64, s70, v[132:133]
	v_lshl_add_u64 v[66:67], v[60:61], 0, s[40:41]
	v_lshl_add_u64 v[60:61], v[66:67], 0, v[128:129]
	global_load_dwordx4 v[60:63], v[60:61], off
	v_lshlrev_b64 v[64:65], 11, v[64:65]
	v_lshl_add_u64 v[64:65], s[28:29], 0, v[64:65]
	v_lshl_add_u64 v[64:65], v[64:65], 0, v[128:129]
	v_lshl_add_u64 v[66:67], v[66:67], 0, v[134:135]
	s_waitcnt vmcnt(0)
; #define GAS __attribute__((address_space(1)))
; #define PG8_BAR __builtin_amdgcn_s_barrier()
; __device__ __forceinline__ u32x4 pack8(f32x4 a, f32x4 b) { u32x4 w; w.x = pk2(a[0], a[1]); w.y = pk2(a[2], a[3]); w.z = pk2(b[0], b[1]); w.w = pk2(b[2], b[3]); return w; }
; __device__ __forceinline__ void unpack8(u32x4 w, f32x4& a, f32x4& b) { a = (f32x4){bf_lo(w.x), bf_hi(w.x), bf_lo(w.y), bf_hi(w.y)}; b = (f32x4){bf_lo(w.z), bf_hi(w.z), bf_lo(w.w), bf_hi(w.w)}; }
; template <class Epi, class Sched>
; __device__ __forceinline__ void gemm_phase(LAS unsigned char* lds, const Gemm g, const Sched& S, const Epi& E, const int wave_) {
;     ...
;         if (wr == 0) PG8_BAR;
;         E(acc, cur, wr, wc, fr, fq);
;         if (!has_next) break;
; #pragma unroll
;         for (int a = 0; a < 2; ++a)
; #pragma unroll
;             for (int b = 0; b < 2; ++b)
; #pragma unroll
;                 for (int m = 0; m < 4; ++m)
; #pragma unroll
;                     for (int n = 0; n < 2; ++n) acc[a][b][m][n] = (f32x4){0.f, 0.f, 0.f, 0.f};
;         cur = nxt; cA = nA; cB = nB; ++ui;
;         if (wr == 1) PG8_BAR;
;     }
;     __device__ __forceinline__ void operator()(const f32x4 (&acc)[2][2][4][2], const Unit& u, int wr, int wc, int fr, int fq) const {
;     ...
;             for (int m = 0; m < 4; ++m) {
;                 const int row = u.pm * 256 + ai * 128 + wr * 64 + m * 16 + fr;
; #pragma unroll
;                 for (int bj = 0; bj < 2; ++bj) {
;                     const int c = u.pn * 256 + bj * 128 + wc * 32 + 8 * fq;
;                     f32x4 g0, g1; unpack8(*(const GAS u32x4*)(Pg + (size_t)row * PW + PC_GATE + 2048 + c), g0, g1);
;                     *(GAS u32x4*)(Mgp + (size_t)row * 1024 + c) = pack8(acc[ai][bj][m][0] * g0, acc[ai][bj][m][1] * g1);
;                 }
;             }
	v_lshlrev_b32_e32 v68, 16, v56
	v_and_b32_e32 v69, 0xffff0000, v56
	v_lshlrev_b32_e32 v56, 16, v57
	v_and_b32_e32 v57, 0xffff0000, v57
	v_lshlrev_b32_e32 v70, 16, v58
	v_and_b32_e32 v71, 0xffff0000, v58
	v_lshlrev_b32_e32 v58, 16, v59
	v_and_b32_e32 v59, 0xffff0000, v59
	v_lshlrev_b32_e32 v72, 16, v60
	v_and_b32_e32 v73, 0xffff0000, v60
	v_lshlrev_b32_e32 v60, 16, v61
	v_and_b32_e32 v61, 0xffff0000, v61
	v_lshlrev_b32_e32 v74, 16, v62
	v_and_b32_e32 v75, 0xffff0000, v62
	v_lshlrev_b32_e32 v62, 16, v63
	v_and_b32_e32 v63, 0xffff0000, v63
	v_pk_mul_f32 v[54:55], v[54:55], v[56:57]
	v_pk_mul_f32 v[52:53], v[52:53], v[68:69]
	v_pk_mul_f32 v[50:51], v[50:51], v[58:59]
	v_pk_mul_f32 v[48:49], v[48:49], v[70:71]
	v_pk_mul_f32 v[46:47], v[46:47], v[60:61]
	v_pk_mul_f32 v[44:45], v[44:45], v[72:73]
	v_pk_mul_f32 v[56:57], v[42:43], v[62:63]
	v_pk_mul_f32 v[58:59], v[40:41], v[74:75]
	v_cvt_pk_bf16_f32 v40, v52, v53
	v_cvt_pk_bf16_f32 v41, v54, v55
	v_cvt_pk_bf16_f32 v42, v48, v49
	v_cvt_pk_bf16_f32 v43, v50, v51
	v_cvt_pk_bf16_f32 v44, v44, v45
	v_cvt_pk_bf16_f32 v45, v46, v47
	v_add_u32_e32 v48, 0xa0, v130
	v_cvt_pk_bf16_f32 v46, v58, v59
	v_cvt_pk_bf16_f32 v47, v56, v57
	global_store_dwordx4 v[80:81], v[40:43], off offset:256
	global_store_dwordx4 v[64:65], v[44:47], off
	global_load_dwordx4 v[40:43], v[66:67], off
	v_ashrrev_i32_e32 v49, 31, v48
	v_mad_i64_i32 v[44:45], s[50:51], v48, s70, v[132:133]
	v_lshl_add_u64 v[50:51], v[44:45], 0, s[40:41]
	v_lshl_add_u64 v[44:45], v[50:51], 0, v[128:129]
	global_load_dwordx4 v[44:47], v[44:45], off
	v_lshlrev_b64 v[48:49], 11, v[48:49]
	v_lshl_add_u64 v[48:49], s[28:29], 0, v[48:49]
	v_lshl_add_u64 v[48:49], v[48:49], 0, v[128:129]
	v_lshl_add_u64 v[50:51], v[50:51], 0, v[134:135]
	s_waitcnt vmcnt(0)
	v_lshlrev_b32_e32 v52, 16, v40
	v_and_b32_e32 v53, 0xffff0000, v40
	v_lshlrev_b32_e32 v40, 16, v41
	v_and_b32_e32 v41, 0xffff0000, v41
	v_lshlrev_b32_e32 v54, 16, v42
	v_and_b32_e32 v55, 0xffff0000, v42
	v_lshlrev_b32_e32 v42, 16, v43
	v_and_b32_e32 v43, 0xffff0000, v43
	v_lshlrev_b32_e32 v56, 16, v44
	v_and_b32_e32 v57, 0xffff0000, v44
	v_lshlrev_b32_e32 v44, 16, v45
	v_and_b32_e32 v45, 0xffff0000, v45
	v_lshlrev_b32_e32 v58, 16, v46
	v_and_b32_e32 v59, 0xffff0000, v46
	v_lshlrev_b32_e32 v46, 16, v47
	v_and_b32_e32 v47, 0xffff0000, v47
	v_pk_mul_f32 v[38:39], v[38:39], v[40:41]
	v_pk_mul_f32 v[36:37], v[36:37], v[52:53]
	v_pk_mul_f32 v[34:35], v[34:35], v[42:43]
	v_pk_mul_f32 v[32:33], v[32:33], v[54:55]
	v_pk_mul_f32 v[30:31], v[30:31], v[44:45]
	v_pk_mul_f32 v[28:29], v[28:29], v[56:57]
	v_pk_mul_f32 v[40:41], v[26:27], v[46:47]
	v_pk_mul_f32 v[42:43], v[24:25], v[58:59]
	v_cvt_pk_bf16_f32 v24, v36, v37
	v_cvt_pk_bf16_f32 v25, v38, v39
	v_cvt_pk_bf16_f32 v26, v32, v33
	v_cvt_pk_bf16_f32 v27, v34, v35
	v_cvt_pk_bf16_f32 v28, v28, v29
	v_cvt_pk_bf16_f32 v29, v30, v31
	v_add_u32_e32 v32, 0xb0, v130
	v_cvt_pk_bf16_f32 v30, v42, v43
	v_cvt_pk_bf16_f32 v31, v40, v41
	global_store_dwordx4 v[64:65], v[24:27], off offset:256
	global_store_dwordx4 v[48:49], v[28:31], off
	global_load_dwordx4 v[24:27], v[50:51], off
	v_ashrrev_i32_e32 v33, 31, v32
	v_mad_i64_i32 v[28:29], s[50:51], v32, s70, v[132:133]
	v_lshl_add_u64 v[34:35], v[28:29], 0, s[40:41]
	v_lshl_add_u64 v[28:29], v[34:35], 0, v[128:129]
	global_load_dwordx4 v[28:31], v[28:29], off
	v_lshlrev_b64 v[32:33], 11, v[32:33]
	v_lshl_add_u64 v[32:33], s[28:29], 0, v[32:33]
	v_lshl_add_u64 v[34:35], v[34:35], 0, v[134:135]
	v_lshl_add_u64 v[32:33], v[32:33], 0, v[128:129]
	s_waitcnt vmcnt(0)
	v_lshlrev_b32_e32 v36, 16, v24
	v_and_b32_e32 v37, 0xffff0000, v24
	v_lshlrev_b32_e32 v24, 16, v25
	v_and_b32_e32 v25, 0xffff0000, v25
	v_lshlrev_b32_e32 v38, 16, v26
	v_and_b32_e32 v39, 0xffff0000, v26
	v_lshlrev_b32_e32 v26, 16, v27
	v_and_b32_e32 v27, 0xffff0000, v27
	v_lshlrev_b32_e32 v40, 16, v28
	v_and_b32_e32 v41, 0xffff0000, v28
	v_lshlrev_b32_e32 v28, 16, v29
	v_and_b32_e32 v29, 0xffff0000, v29
	v_lshlrev_b32_e32 v42, 16, v30
	v_and_b32_e32 v43, 0xffff0000, v30
	v_lshlrev_b32_e32 v30, 16, v31
	v_and_b32_e32 v31, 0xffff0000, v31
	v_pk_mul_f32 v[22:23], v[22:23], v[24:25]
	v_pk_mul_f32 v[20:21], v[20:21], v[36:37]
	v_pk_mul_f32 v[18:19], v[18:19], v[26:27]
	v_pk_mul_f32 v[16:17], v[16:17], v[38:39]
	v_pk_mul_f32 v[14:15], v[14:15], v[28:29]
	v_pk_mul_f32 v[12:13], v[12:13], v[40:41]
	v_pk_mul_f32 v[24:25], v[10:11], v[30:31]
	v_pk_mul_f32 v[26:27], v[8:9], v[42:43]
	v_cvt_pk_bf16_f32 v8, v20, v21
	v_cvt_pk_bf16_f32 v9, v22, v23
	v_cvt_pk_bf16_f32 v10, v16, v17
	v_cvt_pk_bf16_f32 v11, v18, v19
	v_cvt_pk_bf16_f32 v12, v12, v13
	v_cvt_pk_bf16_f32 v13, v14, v15
	v_cvt_pk_bf16_f32 v14, v26, v27
	v_cvt_pk_bf16_f32 v15, v24, v25
	global_store_dwordx4 v[48:49], v[8:11], off offset:256
	global_store_dwordx4 v[32:33], v[12:15], off
	global_load_dwordx4 v[8:11], v[34:35], off
	s_waitcnt vmcnt(0)
	v_lshlrev_b32_e32 v12, 16, v8
	v_and_b32_e32 v13, 0xffff0000, v8
	v_lshlrev_b32_e32 v8, 16, v9
	v_and_b32_e32 v9, 0xffff0000, v9
	v_lshlrev_b32_e32 v14, 16, v10
	v_and_b32_e32 v15, 0xffff0000, v10
	v_lshlrev_b32_e32 v10, 16, v11
	v_and_b32_e32 v11, 0xffff0000, v11
	v_pk_mul_f32 v[6:7], v[6:7], v[8:9]
	v_pk_mul_f32 v[4:5], v[4:5], v[12:13]
	v_pk_mul_f32 v[8:9], v[2:3], v[10:11]
	v_pk_mul_f32 v[2:3], v[0:1], v[14:15]
	v_cvt_pk_bf16_f32 v0, v4, v5
	v_cvt_pk_bf16_f32 v1, v6, v7
	v_cvt_pk_bf16_f32 v2, v2, v3
	v_cvt_pk_bf16_f32 v3, v8, v9
	global_store_dwordx4 v[32:33], v[0:3], off offset:256
	s_cbranch_vccnz .LBB0_1016
	s_andn2_b64 vcc, exec, s[10:11]
	s_cbranch_vccnz .LBB0_1015
	s_barrier
	s_branch .LBB0_1015

; __global__ void __launch_bounds__(512, 2) fwd_mega(Args a) {
	.amdhsa_kernel _Z8fwd_mega4Args
		.amdhsa_group_segment_fixed_size 0
		.amdhsa_private_segment_fixed_size 0
		.amdhsa_kernarg_size 496
		.amdhsa_user_sgpr_count 2
		.amdhsa_user_sgpr_dispatch_ptr 0
		.amdhsa_user_sgpr_queue_ptr 0
		.amdhsa_user_sgpr_kernarg_segment_ptr 1
		.amdhsa_user_sgpr_dispatch_id 0
		.amdhsa_user_sgpr_kernarg_preload_length 0
		.amdhsa_user_sgpr_kernarg_preload_offset 0
		.amdhsa_user_sgpr_private_segment_size 0
		.amdhsa_uses_dynamic_stack 0
		.amdhsa_enable_private_segment 0
		.amdhsa_system_sgpr_workgroup_id_x 1
		.amdhsa_system_sgpr_workgroup_id_y 0
		.amdhsa_system_sgpr_workgroup_id_z 0
		.amdhsa_system_sgpr_workgroup_info 0
		.amdhsa_system_vgpr_workitem_id 2
		.amdhsa_next_free_vgpr 247
		.amdhsa_next_free_sgpr 102
		.amdhsa_accum_offset 248
		.amdhsa_reserve_vcc 1
		.amdhsa_float_round_mode_32 0
		.amdhsa_float_round_mode_16_64 0
		.amdhsa_float_denorm_mode_32 3
		.amdhsa_float_denorm_mode_16_64 3
		.amdhsa_dx10_clamp 1
		.amdhsa_ieee_mode 1
		.amdhsa_fp16_overflow 0
		.amdhsa_tg_split 0
		.amdhsa_exception_fp_ieee_invalid_op 0
		.amdhsa_exception_fp_denorm_src 0
		.amdhsa_exception_fp_ieee_div_zero 0
		.amdhsa_exception_fp_ieee_overflow 0
		.amdhsa_exception_fp_ieee_underflow 0
		.amdhsa_exception_fp_ieee_inexact 0
		.amdhsa_exception_int_div_zero 0
	.end_amdhsa_kernel

; __global__ void __launch_bounds__(512, 2) fwd_mega(Args a) {
.Lfunc_end0:
	.size	_Z8fwd_mega4Args, .Lfunc_end0-_Z8fwd_mega4Args
	.set _Z8fwd_mega4Args.num_vgpr, 247
	.set _Z8fwd_mega4Args.num_agpr, 0
	.set _Z8fwd_mega4Args.numbered_sgpr, 98
	.set _Z8fwd_mega4Args.num_named_barrier, 0
	.set _Z8fwd_mega4Args.private_seg_size, 0
	.set _Z8fwd_mega4Args.uses_vcc, 1
	.set _Z8fwd_mega4Args.uses_flat_scratch, 0
	.set _Z8fwd_mega4Args.has_dyn_sized_stack, 0
	.set _Z8fwd_mega4Args.has_recursion, 0
	.set _Z8fwd_mega4Args.has_indirect_call, 0

; __global__ void __launch_bounds__(512, 2) fwd_mega(Args a) {
amdhsa.kernels:
  - .agpr_count:     0
    .args:
      - .offset:         0
        .size:           240
        .value_kind:     by_value
      - .offset:         240
        .size:           4
        .value_kind:     hidden_block_count_x
      - .offset:         244
        .size:           4
        .value_kind:     hidden_block_count_y
      - .offset:         248
        .size:           4
        .value_kind:     hidden_block_count_z
      - .offset:         252
        .size:           2
        .value_kind:     hidden_group_size_x
      - .offset:         254
        .size:           2
        .value_kind:     hidden_group_size_y
      - .offset:         256
        .size:           2
        .value_kind:     hidden_group_size_z
      - .offset:         258
        .size:           2
        .value_kind:     hidden_remainder_x
      - .offset:         260
        .size:           2
        .value_kind:     hidden_remainder_y
      - .offset:         262
        .size:           2
        .value_kind:     hidden_remainder_z
      - .offset:         280
        .size:           8
        .value_kind:     hidden_global_offset_x
      - .offset:         288
        .size:           8
        .value_kind:     hidden_global_offset_y
      - .offset:         296
        .size:           8
        .value_kind:     hidden_global_offset_z
      - .offset:         304
        .size:           2
        .value_kind:     hidden_grid_dims
      - .offset:         328
        .size:           8
        .value_kind:     hidden_multigrid_sync_arg
      - .offset:         360
        .size:           4
        .value_kind:     hidden_dynamic_lds_size
    .group_segment_fixed_size: 0
    .kernarg_segment_align: 8
    .kernarg_segment_size: 496
    .language:       OpenCL C
    .language_version:
      - 2
      - 0
    .max_flat_workgroup_size: 512
    .name:           _Z8fwd_mega4Args
    .private_segment_fixed_size: 0
    .sgpr_count:     108
    .sgpr_spill_count: 6
    .symbol:         _Z8fwd_mega4Args.kd
    .uniform_work_group_size: 1
    .uses_dynamic_stack: false
    .vgpr_count:     247
    .vgpr_spill_count: 0
    .wavefront_size: 64
